# diff2 X segment: cross-half max exchange only on the rescale path, first two sum terms merged (on top of v23)
# speedup vs baseline: 1.0133x; 1.0133x over previous
; #define LAS __attribute__((address_space(3)))
; __device__ __forceinline__ void d2_softmax(v16f& S, const float c1, const LAS float* tp, float& m, float& l, v16f (&O)[4], v8s (&P)[2]) {
;     float tmax = NEGBIG;
; #pragma unroll
;     for (int i = 0; i < 16; ++i) { S[i] = S[i] * c1 + tp[(i & 3) + 8 * (i >> 2)]; tmax = fmaxf(tmax, S[i]); }
;     tmax = fmaxf(tmax, __shfl_xor(tmax, 32));
;     const float mo = m;
;     if (__any(tmax > mo + 8.f)) {
;         const float mn = (tmax > mo + 8.f) ? tmax : mo;
;         const float alpha = __builtin_amdgcn_exp2f(mo - mn);
;         l *= alpha;
; #pragma unroll
;         for (int eb = 0; eb < 4; ++eb)
; #pragma unroll
;             for (int i = 0; i < 16; ++i) O[eb][i] *= alpha;
;         m = mn;
;     }
;     const float mc = m;
;     float ps = 0.f;
; #pragma unroll
;     for (int i = 0; i < 16; ++i) { S[i] = __builtin_amdgcn_exp2f(S[i] - mc); ps += S[i]; }
;     l += ps;
.Ld2x0_i1d:
	s_bitcmp1_b64 s[100:101], s98
	s_cbranch_scc1 .Ld2x0_c0f
	ds_read2_b32 v[134:135], v0 offset1:1
	ds_read2_b32 v[130:131], v0 offset0:2 offset1:3
	ds_read2_b32 v[132:133], v0 offset0:8 offset1:9
	ds_read2_b32 v[136:137], v0 offset0:10 offset1:11
	ds_read2_b32 v[138:139], v0 offset0:16 offset1:17
	ds_read2_b32 v[140:141], v0 offset0:18 offset1:19
	ds_read2_b32 v[142:143], v0 offset0:24 offset1:25
	s_waitcnt lgkmcnt(6)
	ds_read2_b32 v[144:145], v0 offset0:26 offset1:27
	v_fmac_f32_e32 v135, 0x3e38aa3b, v67
	v_fmamk_f32 v0, v66, 0x3e38aa3b, v134
	v_max3_f32 v66, v0, s15, v135
	s_waitcnt lgkmcnt(6)
	v_fmamk_f32 v68, v68, 0x3e38aa3b, v130
	v_fmac_f32_e32 v131, 0x3e38aa3b, v69
	v_max3_f32 v66, v66, v68, v131
	s_waitcnt lgkmcnt(5)
	v_fmamk_f32 v70, v70, 0x3e38aa3b, v132
	v_fmac_f32_e32 v133, 0x3e38aa3b, v71
	v_max3_f32 v66, v66, v70, v133
	s_waitcnt lgkmcnt(4)
	v_fmamk_f32 v72, v72, 0x3e38aa3b, v136
	v_fmac_f32_e32 v137, 0x3e38aa3b, v73
	v_max3_f32 v66, v66, v72, v137
	s_waitcnt lgkmcnt(3)
	v_fmamk_f32 v74, v74, 0x3e38aa3b, v138
	v_fmac_f32_e32 v139, 0x3e38aa3b, v75
	v_max3_f32 v66, v66, v74, v139
	s_waitcnt lgkmcnt(2)
	v_fmamk_f32 v76, v76, 0x3e38aa3b, v140
	v_fmac_f32_e32 v141, 0x3e38aa3b, v77
	v_max3_f32 v66, v66, v76, v141
	s_waitcnt lgkmcnt(1)
	v_fmamk_f32 v78, v78, 0x3e38aa3b, v142
	v_fmac_f32_e32 v143, 0x3e38aa3b, v79
	v_max3_f32 v66, v66, v78, v143
	s_waitcnt lgkmcnt(0)
	v_fmamk_f32 v80, v80, 0x3e38aa3b, v144
	v_fmac_f32_e32 v145, 0x3e38aa3b, v81
	v_max3_f32 v66, v66, v80, v145
	v_add_f32_e32 v130, 0x41000000, v184
	v_cmp_gt_f32_e32 vcc, v66, v130
	s_cbranch_vccz .Ld2x0_a
	v_mov_b32_e32 v67, v66
	s_nop 1
	v_permlane32_swap_b32_e32 v67, v66
	v_max_f32_e32 v66, v66, v67
	v_cmp_gt_f32_e32 vcc, v66, v130
	s_nop 1
	v_cndmask_b32_e32 v67, v184, v66, vcc
	v_sub_f32_e32 v66, v184, v67
	v_exp_f32_e32 v66, v66
	v_add_f32_e32 v130, 0x41000000, v67
	v_mov_b32_e32 v184, v67
	v_mul_f32_e32 v154, v154, v66
	v_pk_mul_f32 v[64:65], v[64:65], v[66:67] op_sel_hi:[1,0]
	v_pk_mul_f32 v[62:63], v[62:63], v[66:67] op_sel_hi:[1,0]
	v_pk_mul_f32 v[60:61], v[60:61], v[66:67] op_sel_hi:[1,0]
	v_pk_mul_f32 v[58:59], v[58:59], v[66:67] op_sel_hi:[1,0]
	v_pk_mul_f32 v[56:57], v[56:57], v[66:67] op_sel_hi:[1,0]
	v_pk_mul_f32 v[54:55], v[54:55], v[66:67] op_sel_hi:[1,0]
	v_pk_mul_f32 v[52:53], v[52:53], v[66:67] op_sel_hi:[1,0]
	v_pk_mul_f32 v[50:51], v[50:51], v[66:67] op_sel_hi:[1,0]
	v_pk_mul_f32 v[48:49], v[48:49], v[66:67] op_sel_hi:[1,0]
	v_pk_mul_f32 v[46:47], v[46:47], v[66:67] op_sel_hi:[1,0]
	v_pk_mul_f32 v[44:45], v[44:45], v[66:67] op_sel_hi:[1,0]
	v_pk_mul_f32 v[42:43], v[42:43], v[66:67] op_sel_hi:[1,0]
	v_pk_mul_f32 v[40:41], v[40:41], v[66:67] op_sel_hi:[1,0]
	v_pk_mul_f32 v[38:39], v[38:39], v[66:67] op_sel_hi:[1,0]
	v_pk_mul_f32 v[36:37], v[36:37], v[66:67] op_sel_hi:[1,0]
	v_pk_mul_f32 v[34:35], v[34:35], v[66:67] op_sel_hi:[1,0]
	v_pk_mul_f32 v[32:33], v[32:33], v[66:67] op_sel_hi:[1,0]
	v_pk_mul_f32 v[30:31], v[30:31], v[66:67] op_sel_hi:[1,0]
	v_pk_mul_f32 v[28:29], v[28:29], v[66:67] op_sel_hi:[1,0]
	v_pk_mul_f32 v[26:27], v[26:27], v[66:67] op_sel_hi:[1,0]
	v_pk_mul_f32 v[24:25], v[24:25], v[66:67] op_sel_hi:[1,0]
	v_pk_mul_f32 v[22:23], v[22:23], v[66:67] op_sel_hi:[1,0]
	v_pk_mul_f32 v[20:21], v[20:21], v[66:67] op_sel_hi:[1,0]
	v_pk_mul_f32 v[18:19], v[18:19], v[66:67] op_sel_hi:[1,0]
	v_pk_mul_f32 v[16:17], v[16:17], v[66:67] op_sel_hi:[1,0]
	v_pk_mul_f32 v[14:15], v[14:15], v[66:67] op_sel_hi:[1,0]
	v_pk_mul_f32 v[12:13], v[12:13], v[66:67] op_sel_hi:[1,0]
	v_pk_mul_f32 v[10:11], v[10:11], v[66:67] op_sel_hi:[1,0]
	v_pk_mul_f32 v[8:9], v[8:9], v[66:67] op_sel_hi:[1,0]
	v_pk_mul_f32 v[6:7], v[6:7], v[66:67] op_sel_hi:[1,0]
	v_pk_mul_f32 v[4:5], v[4:5], v[66:67] op_sel_hi:[1,0]
	v_pk_mul_f32 v[2:3], v[2:3], v[66:67] op_sel_hi:[1,0]
.Ld2x0_a:
	v_sub_f32_e32 v66, v0, v184
	v_exp_f32_e32 v66, v66
	v_sub_f32_e32 v67, v135, v184
	v_exp_f32_e32 v67, v67
	v_sub_f32_e32 v68, v68, v184
	v_exp_f32_e32 v68, v68
	v_sub_f32_e32 v69, v131, v184
	v_exp_f32_e32 v69, v69
	v_sub_f32_e32 v70, v70, v184
	v_exp_f32_e32 v70, v70
	v_sub_f32_e32 v71, v133, v184
	v_add_f32_e32 v0, v66, v67
	v_exp_f32_e32 v71, v71
	v_sub_f32_e32 v72, v72, v184
	v_add_f32_e32 v0, v68, v0
	v_exp_f32_e32 v72, v72
	v_sub_f32_e32 v73, v137, v184
	v_add_f32_e32 v0, v69, v0
	v_exp_f32_e32 v73, v73
	v_sub_f32_e32 v74, v74, v184
	v_add_f32_e32 v0, v70, v0
	v_exp_f32_e32 v74, v74
	v_sub_f32_e32 v75, v139, v184
	v_add_f32_e32 v0, v71, v0
	v_exp_f32_e32 v75, v75
	v_sub_f32_e32 v76, v76, v184
	v_add_f32_e32 v0, v72, v0
	v_exp_f32_e32 v76, v76
	v_sub_f32_e32 v77, v141, v184
	v_add_f32_e32 v0, v73, v0
	v_exp_f32_e32 v77, v77
	v_sub_f32_e32 v78, v78, v184
	v_add_f32_e32 v0, v74, v0
	v_exp_f32_e32 v78, v78
	v_sub_f32_e32 v79, v143, v184
	v_add_f32_e32 v0, v75, v0
	v_exp_f32_e32 v79, v79
	v_sub_f32_e32 v80, v80, v184
	v_add_f32_e32 v0, v76, v0
	v_exp_f32_e32 v80, v80
	v_sub_f32_e32 v81, v145, v184
	v_add_f32_e32 v0, v77, v0
	v_exp_f32_e32 v81, v81
	s_branch .Ld2x0_s0t
; #define LAS __attribute__((address_space(3)))
; __device__ __forceinline__ void d2_softmax(v16f& S, const float c1, const LAS float* tp, float& m, float& l, v16f (&O)[4], v8s (&P)[2]) {
;     float tmax = NEGBIG;
; #pragma unroll
;     for (int i = 0; i < 16; ++i) { S[i] = S[i] * c1 + tp[(i & 3) + 8 * (i >> 2)]; tmax = fmaxf(tmax, S[i]); }
;     tmax = fmaxf(tmax, __shfl_xor(tmax, 32));
;     const float mo = m;
;     if (__any(tmax > mo + 8.f)) {
;         const float mn = (tmax > mo + 8.f) ? tmax : mo;
;         const float alpha = __builtin_amdgcn_exp2f(mo - mn);
;         l *= alpha;
; #pragma unroll
;         for (int eb = 0; eb < 4; ++eb)
; #pragma unroll
;             for (int i = 0; i < 16; ++i) O[eb][i] *= alpha;
;         m = mn;
;     }
;     const float mc = m;
;     float ps = 0.f;
; #pragma unroll
;     for (int i = 0; i < 16; ++i) { S[i] = __builtin_amdgcn_exp2f(S[i] - mc); ps += S[i]; }
;     l += ps;
.Ld2x0_c0f:
	ds_read_b32 v134, v0
	v_max3_f32 v135, v66, v67, v68
	v_max3_f32 v135, v135, v69, v70
	v_max3_f32 v135, v135, v71, v72
	v_max3_f32 v135, v135, v73, v74
	v_max3_f32 v135, v135, v75, v76
	v_max3_f32 v135, v135, v77, v78
	v_max3_f32 v135, v135, v79, v80
	v_max_f32_e32 v135, v135, v81
	v_add_f32_e32 v130, 0x41000000, v184
	s_waitcnt lgkmcnt(0)
	v_fmamk_f32 v135, v135, 0x3e38aa3b, v134
	v_cmp_gt_f32_e32 vcc, v135, v130
	s_cbranch_vccz .Ld2x0_f0a
	v_mov_b32_e32 v136, v135
	s_nop 1
	v_permlane32_swap_b32_e32 v136, v135
	v_max_f32_e32 v135, v135, v136
	v_cmp_gt_f32_e32 vcc, v135, v130
	s_nop 1
	v_cndmask_b32_e32 v137, v184, v135, vcc
	v_sub_f32_e32 v136, v184, v137
	v_exp_f32_e32 v136, v136
	v_add_f32_e32 v130, 0x41000000, v137
	v_mov_b32_e32 v184, v137
	v_mul_f32_e32 v154, v154, v136
	v_pk_mul_f32 v[64:65], v[64:65], v[136:137] op_sel_hi:[1,0]
	v_pk_mul_f32 v[62:63], v[62:63], v[136:137] op_sel_hi:[1,0]
	v_pk_mul_f32 v[60:61], v[60:61], v[136:137] op_sel_hi:[1,0]
	v_pk_mul_f32 v[58:59], v[58:59], v[136:137] op_sel_hi:[1,0]
	v_pk_mul_f32 v[56:57], v[56:57], v[136:137] op_sel_hi:[1,0]
	v_pk_mul_f32 v[54:55], v[54:55], v[136:137] op_sel_hi:[1,0]
	v_pk_mul_f32 v[52:53], v[52:53], v[136:137] op_sel_hi:[1,0]
	v_pk_mul_f32 v[50:51], v[50:51], v[136:137] op_sel_hi:[1,0]
	v_pk_mul_f32 v[48:49], v[48:49], v[136:137] op_sel_hi:[1,0]
	v_pk_mul_f32 v[46:47], v[46:47], v[136:137] op_sel_hi:[1,0]
	v_pk_mul_f32 v[44:45], v[44:45], v[136:137] op_sel_hi:[1,0]
	v_pk_mul_f32 v[42:43], v[42:43], v[136:137] op_sel_hi:[1,0]
	v_pk_mul_f32 v[40:41], v[40:41], v[136:137] op_sel_hi:[1,0]
	v_pk_mul_f32 v[38:39], v[38:39], v[136:137] op_sel_hi:[1,0]
	v_pk_mul_f32 v[36:37], v[36:37], v[136:137] op_sel_hi:[1,0]
	v_pk_mul_f32 v[34:35], v[34:35], v[136:137] op_sel_hi:[1,0]
	v_pk_mul_f32 v[32:33], v[32:33], v[136:137] op_sel_hi:[1,0]
	v_pk_mul_f32 v[30:31], v[30:31], v[136:137] op_sel_hi:[1,0]
	v_pk_mul_f32 v[28:29], v[28:29], v[136:137] op_sel_hi:[1,0]
	v_pk_mul_f32 v[26:27], v[26:27], v[136:137] op_sel_hi:[1,0]
	v_pk_mul_f32 v[24:25], v[24:25], v[136:137] op_sel_hi:[1,0]
	v_pk_mul_f32 v[22:23], v[22:23], v[136:137] op_sel_hi:[1,0]
	v_pk_mul_f32 v[20:21], v[20:21], v[136:137] op_sel_hi:[1,0]
	v_pk_mul_f32 v[18:19], v[18:19], v[136:137] op_sel_hi:[1,0]
	v_pk_mul_f32 v[16:17], v[16:17], v[136:137] op_sel_hi:[1,0]
	v_pk_mul_f32 v[14:15], v[14:15], v[136:137] op_sel_hi:[1,0]
	v_pk_mul_f32 v[12:13], v[12:13], v[136:137] op_sel_hi:[1,0]
	v_pk_mul_f32 v[10:11], v[10:11], v[136:137] op_sel_hi:[1,0]
	v_pk_mul_f32 v[8:9], v[8:9], v[136:137] op_sel_hi:[1,0]
	v_pk_mul_f32 v[6:7], v[6:7], v[136:137] op_sel_hi:[1,0]
	v_pk_mul_f32 v[4:5], v[4:5], v[136:137] op_sel_hi:[1,0]
	v_pk_mul_f32 v[2:3], v[2:3], v[136:137] op_sel_hi:[1,0]
.Ld2x0_f0a:
	v_sub_f32_e32 v134, v134, v184
	v_fmamk_f32 v66, v66, 0x3e38aa3b, v134
	v_exp_f32_e32 v66, v66
	v_fmamk_f32 v67, v67, 0x3e38aa3b, v134
	v_exp_f32_e32 v67, v67
	v_fmamk_f32 v68, v68, 0x3e38aa3b, v134
	v_exp_f32_e32 v68, v68
	v_fmamk_f32 v69, v69, 0x3e38aa3b, v134
	v_exp_f32_e32 v69, v69
	v_fmamk_f32 v70, v70, 0x3e38aa3b, v134
	v_exp_f32_e32 v70, v70
	v_fmamk_f32 v71, v71, 0x3e38aa3b, v134
	v_add_f32_e32 v0, v66, v67
	v_exp_f32_e32 v71, v71
	v_fmamk_f32 v72, v72, 0x3e38aa3b, v134
	v_add_f32_e32 v0, v68, v0
	v_exp_f32_e32 v72, v72
	v_fmamk_f32 v73, v73, 0x3e38aa3b, v134
	v_add_f32_e32 v0, v69, v0
	v_exp_f32_e32 v73, v73
	v_fmamk_f32 v74, v74, 0x3e38aa3b, v134
	v_add_f32_e32 v0, v70, v0
	v_exp_f32_e32 v74, v74
	v_fmamk_f32 v75, v75, 0x3e38aa3b, v134
	v_add_f32_e32 v0, v71, v0
	v_exp_f32_e32 v75, v75
	v_fmamk_f32 v76, v76, 0x3e38aa3b, v134
	v_add_f32_e32 v0, v72, v0
	v_exp_f32_e32 v76, v76
	v_fmamk_f32 v77, v77, 0x3e38aa3b, v134
	v_add_f32_e32 v0, v73, v0
	v_exp_f32_e32 v77, v77
	v_fmamk_f32 v78, v78, 0x3e38aa3b, v134
	v_add_f32_e32 v0, v74, v0
	v_exp_f32_e32 v78, v78
	v_fmamk_f32 v79, v79, 0x3e38aa3b, v134
	v_add_f32_e32 v0, v75, v0
	v_exp_f32_e32 v79, v79
	v_fmamk_f32 v80, v80, 0x3e38aa3b, v134
	v_add_f32_e32 v0, v76, v0
	v_exp_f32_e32 v80, v80
	v_fmamk_f32 v81, v81, 0x3e38aa3b, v134
	v_add_f32_e32 v0, v77, v0
	v_exp_f32_e32 v81, v81
.Ld2x0_s0t:
	v_add_f32_e32 v0, v78, v0
	v_add_f32_e32 v0, v79, v0
	v_add_f32_e32 v0, v80, v0
	v_add_f32_e32 v0, v81, v0
	v_add_f32_e32 v0, v154, v0
	s_waitcnt lgkmcnt(0)
	s_bitcmp1_b64 s[100:101], s99
	s_cbranch_scc1 .Ld2x0_c1f
	v_fmamk_f32 v82, v82, 0x3e38aa3b, v186
	v_fmac_f32_e32 v187, 0x3e38aa3b, v83
	v_max3_f32 v83, v82, s15, v187
	v_fmamk_f32 v84, v84, 0x3e38aa3b, v188
	v_fmac_f32_e32 v189, 0x3e38aa3b, v85
	v_max3_f32 v83, v83, v84, v189
	v_fmamk_f32 v86, v86, 0x3e38aa3b, v190
	v_fmac_f32_e32 v191, 0x3e38aa3b, v87
	v_max3_f32 v83, v83, v86, v191
	v_fmamk_f32 v88, v88, 0x3e38aa3b, v192
	v_fmac_f32_e32 v193, 0x3e38aa3b, v89
	v_max3_f32 v83, v83, v88, v193
	v_fmamk_f32 v90, v90, 0x3e38aa3b, v194
	v_fmac_f32_e32 v195, 0x3e38aa3b, v91
	v_max3_f32 v83, v83, v90, v195
	v_fmamk_f32 v92, v92, 0x3e38aa3b, v196
	v_fmac_f32_e32 v197, 0x3e38aa3b, v93
	v_max3_f32 v83, v83, v92, v197
	v_fmamk_f32 v94, v94, 0x3e38aa3b, v198
	v_fmac_f32_e32 v199, 0x3e38aa3b, v95
	v_max3_f32 v83, v83, v94, v199
	v_fmamk_f32 v96, v96, 0x3e38aa3b, v200
	v_fmac_f32_e32 v201, 0x3e38aa3b, v97
	v_max3_f32 v83, v83, v96, v201
	v_cmp_gt_f32_e32 vcc, v83, v130
	s_cbranch_vccz .Ld2x0_b
; #define LAS __attribute__((address_space(3)))
; __device__ __forceinline__ void d2_softmax(v16f& S, const float c1, const LAS float* tp, float& m, float& l, v16f (&O)[4], v8s (&P)[2]) {
;     float tmax = NEGBIG;
; #pragma unroll
;     for (int i = 0; i < 16; ++i) { S[i] = S[i] * c1 + tp[(i & 3) + 8 * (i >> 2)]; tmax = fmaxf(tmax, S[i]); }
;     tmax = fmaxf(tmax, __shfl_xor(tmax, 32));
;     const float mo = m;
;     if (__any(tmax > mo + 8.f)) {
;         const float mn = (tmax > mo + 8.f) ? tmax : mo;
;         const float alpha = __builtin_amdgcn_exp2f(mo - mn);
;         l *= alpha;
; #pragma unroll
;         for (int eb = 0; eb < 4; ++eb)
; #pragma unroll
;             for (int i = 0; i < 16; ++i) O[eb][i] *= alpha;
;         m = mn;
;     }
;     const float mc = m;
;     float ps = 0.f;
; #pragma unroll
;     for (int i = 0; i < 16; ++i) { S[i] = __builtin_amdgcn_exp2f(S[i] - mc); ps += S[i]; }
;     l += ps;
	v_mov_b32_e32 v85, v83
	s_nop 1
	v_permlane32_swap_b32_e32 v85, v83
	v_max_f32_e32 v83, v83, v85
	v_cmp_gt_f32_e32 vcc, v83, v130
	s_nop 1
	v_cndmask_b32_e32 v83, v184, v83, vcc
	v_sub_f32_e32 v85, v184, v83
	v_exp_f32_e32 v130, v85
	v_mov_b32_e32 v184, v83
	v_mul_f32_e32 v0, v0, v130
	v_pk_mul_f32 v[64:65], v[64:65], v[130:131] op_sel_hi:[1,0]
	v_pk_mul_f32 v[62:63], v[62:63], v[130:131] op_sel_hi:[1,0]
	v_pk_mul_f32 v[60:61], v[60:61], v[130:131] op_sel_hi:[1,0]
	v_pk_mul_f32 v[58:59], v[58:59], v[130:131] op_sel_hi:[1,0]
	v_pk_mul_f32 v[56:57], v[56:57], v[130:131] op_sel_hi:[1,0]
	v_pk_mul_f32 v[54:55], v[54:55], v[130:131] op_sel_hi:[1,0]
	v_pk_mul_f32 v[52:53], v[52:53], v[130:131] op_sel_hi:[1,0]
	v_pk_mul_f32 v[50:51], v[50:51], v[130:131] op_sel_hi:[1,0]
	v_pk_mul_f32 v[48:49], v[48:49], v[130:131] op_sel_hi:[1,0]
	v_pk_mul_f32 v[46:47], v[46:47], v[130:131] op_sel_hi:[1,0]
	v_pk_mul_f32 v[44:45], v[44:45], v[130:131] op_sel_hi:[1,0]
	v_pk_mul_f32 v[42:43], v[42:43], v[130:131] op_sel_hi:[1,0]
	v_pk_mul_f32 v[40:41], v[40:41], v[130:131] op_sel_hi:[1,0]
	v_pk_mul_f32 v[38:39], v[38:39], v[130:131] op_sel_hi:[1,0]
	v_pk_mul_f32 v[36:37], v[36:37], v[130:131] op_sel_hi:[1,0]
	v_pk_mul_f32 v[34:35], v[34:35], v[130:131] op_sel_hi:[1,0]
	v_pk_mul_f32 v[32:33], v[32:33], v[130:131] op_sel_hi:[1,0]
	v_pk_mul_f32 v[30:31], v[30:31], v[130:131] op_sel_hi:[1,0]
	v_pk_mul_f32 v[28:29], v[28:29], v[130:131] op_sel_hi:[1,0]
	v_pk_mul_f32 v[26:27], v[26:27], v[130:131] op_sel_hi:[1,0]
	v_pk_mul_f32 v[24:25], v[24:25], v[130:131] op_sel_hi:[1,0]
	v_pk_mul_f32 v[22:23], v[22:23], v[130:131] op_sel_hi:[1,0]
	v_pk_mul_f32 v[20:21], v[20:21], v[130:131] op_sel_hi:[1,0]
	v_pk_mul_f32 v[18:19], v[18:19], v[130:131] op_sel_hi:[1,0]
	v_pk_mul_f32 v[16:17], v[16:17], v[130:131] op_sel_hi:[1,0]
	v_pk_mul_f32 v[14:15], v[14:15], v[130:131] op_sel_hi:[1,0]
	v_pk_mul_f32 v[12:13], v[12:13], v[130:131] op_sel_hi:[1,0]
	v_pk_mul_f32 v[10:11], v[10:11], v[130:131] op_sel_hi:[1,0]
	v_pk_mul_f32 v[8:9], v[8:9], v[130:131] op_sel_hi:[1,0]
	v_pk_mul_f32 v[6:7], v[6:7], v[130:131] op_sel_hi:[1,0]
	v_pk_mul_f32 v[4:5], v[4:5], v[130:131] op_sel_hi:[1,0]
	v_pk_mul_f32 v[2:3], v[2:3], v[130:131] op_sel_hi:[1,0]
.Ld2x0_b:
	v_sub_f32_e32 v82, v82, v184
	v_exp_f32_e32 v82, v82
	v_sub_f32_e32 v83, v187, v184
	v_exp_f32_e32 v83, v83
	v_sub_f32_e32 v84, v84, v184
	v_exp_f32_e32 v84, v84
	v_sub_f32_e32 v85, v189, v184
	v_exp_f32_e32 v85, v85
	v_sub_f32_e32 v86, v86, v184
	v_exp_f32_e32 v86, v86
	v_sub_f32_e32 v87, v191, v184
	v_add_f32_e32 v156, v82, v83
	v_exp_f32_e32 v87, v87
	v_sub_f32_e32 v88, v88, v184
	v_add_f32_e32 v156, v84, v156
	v_exp_f32_e32 v88, v88
	v_sub_f32_e32 v89, v193, v184
	v_add_f32_e32 v156, v85, v156
	v_exp_f32_e32 v89, v89
	v_sub_f32_e32 v90, v90, v184
	v_add_f32_e32 v156, v86, v156
	v_exp_f32_e32 v90, v90
	v_sub_f32_e32 v91, v195, v184
	v_add_f32_e32 v156, v87, v156
	v_exp_f32_e32 v91, v91
	v_sub_f32_e32 v92, v92, v184
	v_add_f32_e32 v156, v88, v156
	v_exp_f32_e32 v92, v92
	v_sub_f32_e32 v93, v197, v184
	v_add_f32_e32 v156, v89, v156
	v_exp_f32_e32 v93, v93
	v_sub_f32_e32 v94, v94, v184
	v_add_f32_e32 v156, v90, v156
	v_exp_f32_e32 v94, v94
	v_sub_f32_e32 v95, v199, v184
	v_add_f32_e32 v156, v91, v156
	v_exp_f32_e32 v95, v95
	v_sub_f32_e32 v96, v96, v184
	v_add_f32_e32 v156, v92, v156
	v_exp_f32_e32 v96, v96
	v_sub_f32_e32 v97, v201, v184
	v_add_f32_e32 v156, v93, v156
	v_exp_f32_e32 v97, v97
	s_branch .Ld2x0_cv
; #define LAS __attribute__((address_space(3)))
; __device__ __forceinline__ void d2_softmax(v16f& S, const float c1, const LAS float* tp, float& m, float& l, v16f (&O)[4], v8s (&P)[2]) {
;     float tmax = NEGBIG;
; #pragma unroll
;     for (int i = 0; i < 16; ++i) { S[i] = S[i] * c1 + tp[(i & 3) + 8 * (i >> 2)]; tmax = fmaxf(tmax, S[i]); }
;     tmax = fmaxf(tmax, __shfl_xor(tmax, 32));
;     const float mo = m;
;     if (__any(tmax > mo + 8.f)) {
;         const float mn = (tmax > mo + 8.f) ? tmax : mo;
;         const float alpha = __builtin_amdgcn_exp2f(mo - mn);
;         l *= alpha;
; #pragma unroll
;         for (int eb = 0; eb < 4; ++eb)
; #pragma unroll
;             for (int i = 0; i < 16; ++i) O[eb][i] *= alpha;
;         m = mn;
;     }
;     const float mc = m;
;     float ps = 0.f;
; #pragma unroll
;     for (int i = 0; i < 16; ++i) { S[i] = __builtin_amdgcn_exp2f(S[i] - mc); ps += S[i]; }
;     l += ps;
.Ld2x0_c1f:
	v_max3_f32 v158, v82, v83, v84
	v_max3_f32 v158, v158, v85, v86
	v_max3_f32 v158, v158, v87, v88
	v_max3_f32 v158, v158, v89, v90
	v_max3_f32 v158, v158, v91, v92
	v_max3_f32 v158, v158, v93, v94
	v_max3_f32 v158, v158, v95, v96
	v_max_f32_e32 v158, v158, v97
	v_fmamk_f32 v158, v158, 0x3e38aa3b, v186
	v_cmp_gt_f32_e32 vcc, v158, v130
	s_cbranch_vccz .Ld2x0_f1a
	v_mov_b32_e32 v159, v158
	s_nop 1
	v_permlane32_swap_b32_e32 v159, v158
	v_max_f32_e32 v158, v158, v159
	v_cmp_gt_f32_e32 vcc, v158, v130
	s_nop 1
	v_cndmask_b32_e32 v159, v184, v158, vcc
	v_sub_f32_e32 v158, v184, v159
	v_exp_f32_e32 v158, v158
	v_mov_b32_e32 v184, v159
	v_mul_f32_e32 v0, v0, v158
	v_pk_mul_f32 v[64:65], v[64:65], v[158:159] op_sel_hi:[1,0]
	v_pk_mul_f32 v[62:63], v[62:63], v[158:159] op_sel_hi:[1,0]
	v_pk_mul_f32 v[60:61], v[60:61], v[158:159] op_sel_hi:[1,0]
	v_pk_mul_f32 v[58:59], v[58:59], v[158:159] op_sel_hi:[1,0]
	v_pk_mul_f32 v[56:57], v[56:57], v[158:159] op_sel_hi:[1,0]
	v_pk_mul_f32 v[54:55], v[54:55], v[158:159] op_sel_hi:[1,0]
	v_pk_mul_f32 v[52:53], v[52:53], v[158:159] op_sel_hi:[1,0]
	v_pk_mul_f32 v[50:51], v[50:51], v[158:159] op_sel_hi:[1,0]
	v_pk_mul_f32 v[48:49], v[48:49], v[158:159] op_sel_hi:[1,0]
	v_pk_mul_f32 v[46:47], v[46:47], v[158:159] op_sel_hi:[1,0]
	v_pk_mul_f32 v[44:45], v[44:45], v[158:159] op_sel_hi:[1,0]
	v_pk_mul_f32 v[42:43], v[42:43], v[158:159] op_sel_hi:[1,0]
	v_pk_mul_f32 v[40:41], v[40:41], v[158:159] op_sel_hi:[1,0]
	v_pk_mul_f32 v[38:39], v[38:39], v[158:159] op_sel_hi:[1,0]
	v_pk_mul_f32 v[36:37], v[36:37], v[158:159] op_sel_hi:[1,0]
	v_pk_mul_f32 v[34:35], v[34:35], v[158:159] op_sel_hi:[1,0]
	v_pk_mul_f32 v[32:33], v[32:33], v[158:159] op_sel_hi:[1,0]
	v_pk_mul_f32 v[30:31], v[30:31], v[158:159] op_sel_hi:[1,0]
	v_pk_mul_f32 v[28:29], v[28:29], v[158:159] op_sel_hi:[1,0]
	v_pk_mul_f32 v[26:27], v[26:27], v[158:159] op_sel_hi:[1,0]
	v_pk_mul_f32 v[24:25], v[24:25], v[158:159] op_sel_hi:[1,0]
	v_pk_mul_f32 v[22:23], v[22:23], v[158:159] op_sel_hi:[1,0]
	v_pk_mul_f32 v[20:21], v[20:21], v[158:159] op_sel_hi:[1,0]
	v_pk_mul_f32 v[18:19], v[18:19], v[158:159] op_sel_hi:[1,0]
	v_pk_mul_f32 v[16:17], v[16:17], v[158:159] op_sel_hi:[1,0]
	v_pk_mul_f32 v[14:15], v[14:15], v[158:159] op_sel_hi:[1,0]
	v_pk_mul_f32 v[12:13], v[12:13], v[158:159] op_sel_hi:[1,0]
	v_pk_mul_f32 v[10:11], v[10:11], v[158:159] op_sel_hi:[1,0]
	v_pk_mul_f32 v[8:9], v[8:9], v[158:159] op_sel_hi:[1,0]
	v_pk_mul_f32 v[6:7], v[6:7], v[158:159] op_sel_hi:[1,0]
	v_pk_mul_f32 v[4:5], v[4:5], v[158:159] op_sel_hi:[1,0]
	v_pk_mul_f32 v[2:3], v[2:3], v[158:159] op_sel_hi:[1,0]
.Ld2x0_f1a:
	v_sub_f32_e32 v186, v186, v184
	v_fmamk_f32 v82, v82, 0x3e38aa3b, v186
	v_exp_f32_e32 v82, v82
	v_fmamk_f32 v83, v83, 0x3e38aa3b, v186
	v_exp_f32_e32 v83, v83
	v_fmamk_f32 v84, v84, 0x3e38aa3b, v186
	v_exp_f32_e32 v84, v84
	v_fmamk_f32 v85, v85, 0x3e38aa3b, v186
	v_exp_f32_e32 v85, v85
	v_fmamk_f32 v86, v86, 0x3e38aa3b, v186
	v_exp_f32_e32 v86, v86
	v_fmamk_f32 v87, v87, 0x3e38aa3b, v186
	v_add_f32_e32 v156, v82, v83
	v_exp_f32_e32 v87, v87
	v_fmamk_f32 v88, v88, 0x3e38aa3b, v186
	v_add_f32_e32 v156, v84, v156
	v_exp_f32_e32 v88, v88
	v_fmamk_f32 v89, v89, 0x3e38aa3b, v186
	v_add_f32_e32 v156, v85, v156
	v_exp_f32_e32 v89, v89
	v_fmamk_f32 v90, v90, 0x3e38aa3b, v186
	v_add_f32_e32 v156, v86, v156
	v_exp_f32_e32 v90, v90
	v_fmamk_f32 v91, v91, 0x3e38aa3b, v186
	v_add_f32_e32 v156, v87, v156
	v_exp_f32_e32 v91, v91
	v_fmamk_f32 v92, v92, 0x3e38aa3b, v186
	v_add_f32_e32 v156, v88, v156
	v_exp_f32_e32 v92, v92
	v_fmamk_f32 v93, v93, 0x3e38aa3b, v186
	v_add_f32_e32 v156, v89, v156
	v_exp_f32_e32 v93, v93
	v_fmamk_f32 v94, v94, 0x3e38aa3b, v186
	v_add_f32_e32 v156, v90, v156
	v_exp_f32_e32 v94, v94
	v_fmamk_f32 v95, v95, 0x3e38aa3b, v186
	v_add_f32_e32 v156, v91, v156
	v_exp_f32_e32 v95, v95
	v_fmamk_f32 v96, v96, 0x3e38aa3b, v186
	v_add_f32_e32 v156, v92, v156
	v_exp_f32_e32 v96, v96
	v_fmamk_f32 v97, v97, 0x3e38aa3b, v186
	v_add_f32_e32 v156, v93, v156
	v_exp_f32_e32 v97, v97
